# top-k threshold search: compare results rotated over four SGPR pairs so the 17 hazard nops per bit iteration disappear
# baseline (speedup 1.0000x reference)
; __device__ __forceinline__ void unitA(unsigned char* lds, PG8_LAS unsigned char* lds3, const Args& a, int b, int g, int T) {
;     ...
;                 const unsigned cand = thr | (1u << bit);
;                 int cnt = 0;
; #pragma unroll
;                 for (int i = 0; i < 16; ++i) cnt += (u[i] >= cand) ? 1 : 0;
;                 cnt += __builtin_amdgcn_update_dpp(0, cnt, 0xB1, 0xF, 0xF, true); cnt += __builtin_amdgcn_update_dpp(0, cnt, 0x4E, 0xF, 0xF, true); cnt += __builtin_amdgcn_update_dpp(0, cnt, 0x141, 0xF, 0xF, true);
;                 if (cnt >= 13) thr = cand;
;             }
;             int ngt = 0, neq = 0;
; #pragma unroll
;             for (int i = 0; i < 16; ++i) { const int j = 16 * gq + i; ngt += (u[i] > thr) ? 1 : 0; neq += (u[i] == thr && j >= 1 && j <= T - 2) ? 1 : 0; }
;             ngt += __builtin_amdgcn_update_dpp(0, ngt, 0xB1, 0xF, 0xF, true); ngt += __builtin_amdgcn_update_dpp(0, ngt, 0x4E, 0xF, 0xF, true); ngt += __builtin_amdgcn_update_dpp(0, ngt, 0x141, 0xF, 0xF, true);
;             int before = 0;
; #pragma unroll
;             for (int g2 = 0; g2 < 7; ++g2) { const int other = __shfl(neq, (lane & ~7) | g2); before += (g2 < gq) ? other : 0; }
;             int need = 13 - ngt - before;
; #pragma unroll
;             for (int i = 0; i < 16; ++i) {
;                 const int j = 16 * gq + i; bool sel = u[i] > thr;
.LBB0_2464:
	s_lshl_b32 s4, 1, s1
	v_or_b32_e32 v83, s4, v76
	s_waitcnt lgkmcnt(0)
	s_add_i32 s1, s1, -1
	s_cmp_eq_u32 s1, -1
	v_cmp_ge_u32_e64 s[10:11], v66, v83
	v_cmp_ge_u32_e64 s[12:13], v67, v83
	v_cmp_ge_u32_e64 s[98:99], v69, v83
	v_cmp_ge_u32_e64 s[100:101], v68, v83
	v_cndmask_b32_e64 v84, 0, 1, s[10:11]
	v_cmp_ge_u32_e64 s[10:11], v71, v83
	v_addc_co_u32_e64 v84, s[12:13], 0, v84, s[12:13]
	v_cmp_ge_u32_e64 s[12:13], v70, v83
	v_addc_co_u32_e64 v84, s[98:99], 0, v84, s[98:99]
	v_cmp_ge_u32_e64 s[98:99], v73, v83
	v_addc_co_u32_e64 v84, s[100:101], 0, v84, s[100:101]
	v_cmp_ge_u32_e64 s[100:101], v72, v83
	v_addc_co_u32_e64 v84, s[10:11], 0, v84, s[10:11]
	v_cmp_ge_u32_e64 s[10:11], v75, v83
	v_addc_co_u32_e64 v84, s[12:13], 0, v84, s[12:13]
	v_cmp_ge_u32_e64 s[12:13], v74, v83
	v_addc_co_u32_e64 v84, s[98:99], 0, v84, s[98:99]
	v_cmp_ge_u32_e64 s[98:99], v78, v83
	v_addc_co_u32_e64 v84, s[100:101], 0, v84, s[100:101]
	v_cmp_ge_u32_e64 s[100:101], v77, v83
	v_addc_co_u32_e64 v84, s[10:11], 0, v84, s[10:11]
	v_cmp_ge_u32_e64 s[10:11], v81, v83
	v_addc_co_u32_e64 v84, s[12:13], 0, v84, s[12:13]
	v_cmp_ge_u32_e64 s[12:13], v80, v83
	v_addc_co_u32_e64 v84, s[98:99], 0, v84, s[98:99]
	v_cmp_ge_u32_e64 s[98:99], v82, v83
	v_addc_co_u32_e64 v84, s[100:101], 0, v84, s[100:101]
	v_cmp_ge_u32_e64 s[100:101], v79, v83
	v_addc_co_u32_e64 v84, s[10:11], 0, v84, s[10:11]
	v_addc_co_u32_e64 v84, s[12:13], 0, v84, s[12:13]
	v_addc_co_u32_e64 v84, s[98:99], 0, v84, s[98:99]
	v_addc_co_u32_e64 v84, s[100:101], 0, v84, s[100:101]
	s_nop 1
	v_add_u32_dpp v84, v84, v84 quad_perm:[1,0,3,2] row_mask:0xf bank_mask:0xf bound_ctrl:1
	s_nop 1
	v_add_u32_dpp v84, v84, v84 quad_perm:[2,3,0,1] row_mask:0xf bank_mask:0xf bound_ctrl:1
	s_nop 1
	v_add_u32_dpp v84, v84, v84 row_half_mirror row_mask:0xf bank_mask:0xf bound_ctrl:1
	v_cmp_lt_i32_e64 s[10:11], 12, v84
	s_nop 1
	v_cndmask_b32_e64 v76, v76, v83, s[10:11]
	s_cbranch_scc0 .LBB0_2464
	v_cmp_eq_u32_e64 s[10:11], v67, v76
	v_cmp_ne_u32_e64 s[12:13], 0, v146
	s_and_b64 s[6:7], s[12:13], s[10:11]
	v_cmp_gt_u32_e64 s[10:11], v66, v76
	v_cmp_gt_u32_e64 s[46:47], v67, v76
	v_cmp_gt_u32_e64 s[38:39], v68, v76
	v_cndmask_b32_e64 v85, 0, 1, s[10:11]
	v_addc_co_u32_e64 v67, s[10:11], 0, v85, s[46:47]
	v_cmp_eq_u32_e64 s[10:11], v66, v76
	s_and_b64 s[42:43], s[8:9], s[10:11]
	v_cmp_gt_u32_e64 s[8:9], v69, v76
	v_cmp_eq_u32_e64 s[22:23], v68, v76
	v_cmp_gt_u32_e64 s[30:31], v70, v76
	v_cndmask_b32_e64 v86, 0, 1, s[8:9]
	v_addc_co_u32_e64 v67, s[8:9], v67, v86, s[38:39]
	v_cmp_gt_u32_e64 s[8:9], v71, v76
	v_cmp_eq_u32_e64 s[16:17], v69, v76
	v_cmp_gt_u32_e64 s[24:25], v72, v76
	v_cndmask_b32_e64 v68, 0, 1, s[8:9]
	v_addc_co_u32_e64 v67, s[8:9], v67, v68, s[30:31]
	v_cmp_gt_u32_e64 s[8:9], v73, v76
	v_cmp_eq_u32_e64 s[36:37], v70, v76
	v_cmp_gt_u32_e64 s[20:21], v74, v76
	v_cndmask_b32_e64 v69, 0, 1, s[8:9]
	v_addc_co_u32_e64 v67, s[8:9], v67, v69, s[24:25]
	v_cmp_gt_u32_e64 s[8:9], v75, v76
	v_cmp_eq_u32_e64 s[28:29], v71, v76
	v_cmp_gt_u32_e64 s[12:13], v77, v76
	v_cndmask_b32_e64 v70, 0, 1, s[8:9]
	v_addc_co_u32_e64 v67, s[8:9], v67, v70, s[20:21]
	v_cmp_gt_u32_e64 s[8:9], v78, v76
	v_cmp_eq_u32_e64 s[58:59], v72, v76
	v_cmp_gt_u32_e64 s[10:11], v80, v76
	v_cndmask_b32_e64 v71, 0, 1, s[8:9]
	v_addc_co_u32_e64 v67, s[8:9], v67, v71, s[12:13]
	v_cmp_gt_u32_e64 s[8:9], v81, v76
	v_cmp_ge_i32_e64 s[18:19], s93, v52
	v_cmp_ge_i32_e64 s[26:27], s93, v53
	v_cndmask_b32_e64 v72, 0, 1, s[8:9]
	v_addc_co_u32_e64 v67, s[8:9], v67, v72, s[10:11]
	v_cmp_gt_u32_e64 s[8:9], v82, v76
	v_cndmask_b32_e64 v66, 0, 1, s[42:43]
	v_cmp_ge_i32_e64 s[34:35], s93, v54
	v_cmp_ge_i32_e64 s[40:41], s93, v55
	v_cmp_eq_u32_e64 s[44:45], v73, v76
	v_cndmask_b32_e64 v73, 0, 1, s[8:9]
	v_cmp_eq_u32_e64 s[8:9], v79, v76
	v_cmp_ge_i32_e64 s[48:49], s93, v65
	s_and_b64 s[54:55], s[16:17], s[18:19]
	s_and_b64 s[52:53], s[22:23], s[26:27]
	v_cmp_ge_i32_e64 s[56:57], s93, v56
	v_cmp_ge_i32_e64 s[60:61], s93, v57
	v_cmp_eq_u32_e64 s[62:63], v75, v76
	v_cmp_eq_u32_e64 s[74:75], v77, v76
	s_and_b64 s[8:9], s[48:49], s[8:9]
	v_addc_co_u32_e64 v75, s[16:17], 0, v66, s[54:55]
	v_cndmask_b32_e64 v77, 0, 1, s[52:53]
	s_and_b64 s[50:51], s[28:29], s[34:35]
	s_and_b64 s[48:49], s[36:37], s[40:41]
	v_cmp_ge_i32_e64 s[64:65], s93, v58
	v_cmp_eq_u32_e64 s[66:67], v74, v76
	v_cmp_ge_i32_e64 s[68:69], s93, v59
	v_cmp_eq_u32_e64 s[70:71], v78, v76
	v_addc_co_u32_e64 v75, s[16:17], v75, v77, s[50:51]
	v_cndmask_b32_e64 v78, 0, 1, s[48:49]
	s_and_b64 s[44:45], s[44:45], s[56:57]
	s_and_b64 s[40:41], s[58:59], s[60:61]
	v_cmp_ge_i32_e64 s[72:73], s93, v60
	v_cmp_ge_i32_e64 s[76:77], s93, v61
	v_cmp_eq_u32_e64 s[82:83], v80, v76
	v_addc_co_u32_e64 v75, s[16:17], v75, v78, s[44:45]
	v_cndmask_b32_e64 v80, 0, 1, s[40:41]
	s_and_b64 s[36:37], s[62:63], s[64:65]
	s_and_b64 s[34:35], s[66:67], s[68:69]
	v_cmp_eq_u32_e64 s[78:79], v81, v76
	v_cmp_ge_i32_e64 s[80:81], s93, v62
	v_addc_co_u32_e64 v75, s[16:17], v75, v80, s[36:37]
	v_cndmask_b32_e64 v81, 0, 1, s[34:35]
	s_and_b64 s[28:29], s[70:71], s[72:73]
	s_and_b64 s[26:27], s[74:75], s[76:77]
	v_cmp_ge_i32_e64 s[84:85], s93, v63
	v_cmp_eq_u32_e64 s[86:87], v82, v76
	v_addc_co_u32_e64 v75, s[16:17], v75, v81, s[28:29]
	v_cndmask_b32_e64 v82, 0, 1, s[26:27]
	s_and_b64 s[22:23], s[78:79], s[80:81]
	v_cmp_ge_i32_e64 s[88:89], s93, v64
	v_addc_co_u32_e64 v75, s[16:17], v75, v82, s[22:23]
	s_and_b64 s[18:19], s[82:83], s[84:85]
	v_cndmask_b32_e64 v87, 0, 1, s[18:19]
	s_and_b64 s[16:17], s[86:87], s[88:89]
	v_cmp_ge_i32_e64 s[14:15], s93, v19
	v_addc_co_u32_e64 v75, s[56:57], v75, v87, s[16:17]
	v_and_b32_e32 v84, 56, v133
	v_cndmask_b32_e64 v74, 0, 1, s[8:9]
	s_and_b64 s[56:57], s[14:15], s[6:7]
	v_addc_co_u32_e64 v74, s[14:15], v75, v74, s[56:57]
	v_and_or_b32 v75, v163, 64, v84
	v_lshlrev_b32_e32 v75, 2, v75
	ds_bpermute_b32 v84, v75, v74
	v_cmp_gt_u32_e64 s[14:15], v79, v76
	ds_bpermute_b32 v76, v75, v74 offset:4
	ds_bpermute_b32 v88, v75, v74 offset:12
	v_addc_co_u32_e64 v67, s[58:59], v67, v73, s[14:15]
	s_waitcnt lgkmcnt(2)
; __device__ __forceinline__ void unitA(unsigned char* lds, PG8_LAS unsigned char* lds3, const Args& a, int b, int g, int T) {
;     ...
;             int ngt = 0, neq = 0;
; #pragma unroll
;             for (int i = 0; i < 16; ++i) { const int j = 16 * gq + i; ngt += (u[i] > thr) ? 1 : 0; neq += (u[i] == thr && j >= 1 && j <= T - 2) ? 1 : 0; }
;             ngt += __builtin_amdgcn_update_dpp(0, ngt, 0xB1, 0xF, 0xF, true); ngt += __builtin_amdgcn_update_dpp(0, ngt, 0x4E, 0xF, 0xF, true); ngt += __builtin_amdgcn_update_dpp(0, ngt, 0x141, 0xF, 0xF, true);
;             int before = 0;
; #pragma unroll
;             for (int g2 = 0; g2 < 7; ++g2) { const int other = __shfl(neq, (lane & ~7) | g2); before += (g2 < gq) ? other : 0; }
;             int need = 13 - ngt - before;
; #pragma unroll
;             for (int i = 0; i < 16; ++i) {
;                 const int j = 16 * gq + i; bool sel = u[i] > thr;
	v_cndmask_b32_e64 v79, v84, 0, vcc
	ds_bpermute_b32 v84, v75, v74 offset:8
	ds_bpermute_b32 v89, v75, v74 offset:16
	v_cmp_lt_u32_e64 s[58:59], 1, v146
	ds_bpermute_b32 v90, v75, v74 offset:20
	ds_bpermute_b32 v74, v75, v74 offset:24
	s_waitcnt lgkmcnt(5)
	v_cndmask_b32_e64 v76, 0, v76, s[58:59]
	v_cmp_lt_u32_e64 s[58:59], 2, v146
	v_add_u32_dpp v67, v67, v67 quad_perm:[1,0,3,2] row_mask:0xf bank_mask:0xf bound_ctrl:1
	v_or_b32_e32 v83, 1, v19
	s_waitcnt lgkmcnt(3)
	v_cndmask_b32_e64 v84, 0, v84, s[58:59]
	v_cmp_lt_u32_e64 s[58:59], 3, v146
	v_add_u32_dpp v67, v67, v67 quad_perm:[2,3,0,1] row_mask:0xf bank_mask:0xf bound_ctrl:1
	s_mov_b64 s[80:81], s[96:97]
	v_cndmask_b32_e64 v88, 0, v88, s[58:59]
	v_cmp_lt_u32_e64 s[58:59], 4, v146
	v_readlane_b32 s82, v252, 2
	v_readlane_b32 s96, v253, 42
	s_waitcnt lgkmcnt(2)
	v_cndmask_b32_e64 v75, 0, v89, s[58:59]
	v_cmp_lt_u32_e64 s[58:59], 5, v146
	v_readlane_b32 s70, v253, 17
	v_readlane_b32 s68, v253, 0
	s_waitcnt lgkmcnt(1)
	v_cndmask_b32_e64 v89, 0, v90, s[58:59]
	v_mov_b32_dpp v90, v67 row_half_mirror row_mask:0xf bank_mask:0xf bound_ctrl:1
	v_add3_u32 v67, v67, v79, v76
	v_cmp_eq_u32_e64 s[58:59], 7, v146
	v_add3_u32 v67, v67, v84, v88
	v_add3_u32 v67, v67, v75, v89
	s_waitcnt lgkmcnt(0)
	v_cndmask_b32_e64 v74, 0, v74, s[58:59]
	v_add3_u32 v67, v67, v90, v74
	v_sub_u32_e32 v74, 13, v67
	v_subb_co_u32_e64 v67, s[58:59], 13, v67, s[56:57]
	v_cmp_lt_i32_e64 s[58:59], 0, v74
	v_cndmask_b32_e64 v75, 0, 1, s[46:47]
	v_readlane_b32 s84, v253, 53
	v_cndmask_b32_e64 v74, 0, 1, s[58:59]
	v_cndmask_b32_e64 v74, v75, v74, s[56:57]
	v_cmp_eq_u32_e64 s[56:57], s2, v19
	s_or_b64 s[6:7], vcc, s[56:57]
	v_cmp_eq_u32_e32 vcc, s0, v19
	s_or_b64 s[6:7], vcc, s[6:7]
	v_cmp_lt_i32_e32 vcc, 0, v67
	v_and_b32_e32 v74, 1, v74
	v_cmp_eq_u32_e64 s[46:47], 1, v74
	v_cndmask_b32_e64 v76, 0, 1, vcc
	v_cndmask_b32_e64 v76, v85, v76, s[42:43]
	s_or_b64 s[6:7], s[6:7], s[46:47]
	v_and_b32_e32 v76, 1, v76
	v_cmp_eq_u32_e64 s[42:43], s2, v83
	v_cmp_eq_u32_e64 s[46:47], s0, v83
	v_cndmask_b32_e64 v74, 0, 1, s[6:7]
	v_cmp_eq_u32_e32 vcc, 1, v76
	s_or_b64 s[6:7], s[46:47], s[42:43]
	v_sub_u32_e32 v75, v67, v66
	s_or_b64 s[6:7], s[6:7], vcc
	v_subb_co_u32_e64 v66, vcc, v67, v66, s[54:55]
	v_cndmask_b32_e64 v76, 0, 2, s[6:7]
	v_cmp_lt_i32_e32 vcc, 0, v75
	v_or_b32_e32 v74, v76, v74
	v_cmp_eq_u32_e64 s[42:43], s2, v52
	v_cndmask_b32_e64 v76, 0, 1, vcc
	v_cndmask_b32_e64 v76, v86, v76, s[54:55]
	v_and_b32_e32 v76, 1, v76
	v_cmp_eq_u32_e64 s[46:47], s0, v52
	v_cndmask_b32_e64 v67, 0, 1, s[54:55]
	v_cmp_eq_u32_e32 vcc, 1, v76
	s_or_b64 s[6:7], s[46:47], s[42:43]
	s_or_b64 s[6:7], s[6:7], vcc
	v_subb_co_u32_e64 v67, vcc, v75, v67, s[52:53]
	v_cmp_lt_i32_e32 vcc, 0, v66
	v_cndmask_b32_e64 v76, 0, 1, s[38:39]
	s_mov_b32 s46, s2
	v_cndmask_b32_e64 v75, 0, 1, vcc
	v_cndmask_b32_e64 v75, v76, v75, s[52:53]
	v_and_b32_e32 v75, 1, v75
	v_cmp_eq_u32_e64 s[38:39], s46, v53
	v_cmp_eq_u32_e64 s[42:43], s0, v53
	v_cndmask_b32_e64 v52, 0, 4, s[6:7]
	v_cmp_eq_u32_e32 vcc, 1, v75
	s_or_b64 s[6:7], s[42:43], s[38:39]
	s_or_b64 s[6:7], s[6:7], vcc
	v_cndmask_b32_e64 v53, 0, 8, s[6:7]
	v_or3_b32 v52, v74, v52, v53
	v_subb_co_u32_e64 v53, vcc, v66, v77, s[50:51]
	v_cmp_lt_i32_e32 vcc, 0, v67
	v_cmp_eq_u32_e64 s[38:39], s46, v54
	v_cmp_eq_u32_e64 s[42:43], s0, v54
	v_cndmask_b32_e64 v74, 0, 1, vcc
	v_cndmask_b32_e64 v68, v68, v74, s[50:51]
	v_and_b32_e32 v68, 1, v68
	v_cndmask_b32_e64 v66, 0, 1, s[50:51]
	v_cmp_eq_u32_e32 vcc, 1, v68
	s_or_b64 s[6:7], s[42:43], s[38:39]
	s_or_b64 s[6:7], s[6:7], vcc
	v_subb_co_u32_e64 v66, vcc, v67, v66, s[48:49]
	v_cmp_lt_i32_e32 vcc, 0, v53
	v_cndmask_b32_e64 v68, 0, 1, s[30:31]
	v_cmp_eq_u32_e64 s[30:31], s46, v55
	v_cndmask_b32_e64 v67, 0, 1, vcc
	v_cndmask_b32_e64 v67, v68, v67, s[48:49]
	v_and_b32_e32 v67, 1, v67
	v_cmp_eq_u32_e64 s[38:39], s0, v55
	v_cndmask_b32_e64 v54, 0, 16, s[6:7]
	v_cmp_eq_u32_e32 vcc, 1, v67
	s_or_b64 s[6:7], s[38:39], s[30:31]
	s_or_b64 s[6:7], s[6:7], vcc
	v_subb_co_u32_e64 v53, vcc, v53, v78, s[44:45]
	v_cndmask_b32_e64 v55, 0, 32, s[6:7]
	v_cmp_lt_i32_e32 vcc, 0, v66
	v_or3_b32 v52, v52, v54, v55
	v_cmp_eq_u32_e64 s[30:31], s46, v56
	v_cndmask_b32_e64 v55, 0, 1, vcc
	v_cndmask_b32_e64 v55, v69, v55, s[44:45]
	v_and_b32_e32 v55, 1, v55
	v_cmp_eq_u32_e64 s[38:39], s0, v56
	v_cndmask_b32_e64 v54, 0, 1, s[44:45]
	v_cmp_eq_u32_e32 vcc, 1, v55
	s_or_b64 s[6:7], s[38:39], s[30:31]
	s_or_b64 s[6:7], s[6:7], vcc
	v_subb_co_u32_e64 v54, vcc, v66, v54, s[40:41]
	v_cmp_lt_i32_e32 vcc, 0, v53
	v_cndmask_b32_e64 v66, 0, 1, s[24:25]
	v_cmp_eq_u32_e64 s[24:25], s46, v57
	v_cndmask_b32_e64 v56, 0, 1, vcc
	v_cndmask_b32_e64 v56, v66, v56, s[40:41]
	v_and_b32_e32 v56, 1, v56
	v_cmp_eq_u32_e64 s[30:31], s0, v57
; __device__ __forceinline__ void unitA(unsigned char* lds, PG8_LAS unsigned char* lds3, const Args& a, int b, int g, int T) {
;     ...
; #pragma unroll
;             for (int i = 0; i < 16; ++i) {
;                 const int j = 16 * gq + i; bool sel = u[i] > thr;
;     ...
;                 if (j == 0 || j == T - 1 || j == T) sel = true;
;                 m16 |= sel ? (1u << i) : 0u;
;             }
;         }
;         const unsigned hi = (unsigned)__builtin_amdgcn_update_dpp(0, (int)m16, 0xB1, 0xF, 0xF, true);
;         if ((gq & 1) == 0) selm[qi * 4 + (gq >> 1)] = m16 | (hi << 16);
	v_cndmask_b32_e64 v55, 0, 64, s[6:7]
	v_cmp_eq_u32_e32 vcc, 1, v56
	s_or_b64 s[6:7], s[30:31], s[24:25]
	s_or_b64 vcc, s[6:7], vcc
	v_cndmask_b32_e32 v56, 0, v164, vcc
	v_subb_co_u32_e64 v53, vcc, v53, v80, s[36:37]
	v_cmp_lt_i32_e32 vcc, 0, v54
	v_or3_b32 v52, v52, v55, v56
	v_cmp_eq_u32_e64 s[24:25], s46, v58
	v_cndmask_b32_e64 v56, 0, 1, vcc
	v_cndmask_b32_e64 v56, v70, v56, s[36:37]
	v_and_b32_e32 v56, 1, v56
	v_cmp_eq_u32_e64 s[30:31], s0, v58
	v_cmp_eq_u32_e32 vcc, 1, v56
	s_or_b64 s[6:7], s[30:31], s[24:25]
	v_cndmask_b32_e64 v55, 0, 1, s[36:37]
	s_or_b64 vcc, s[6:7], vcc
	v_cndmask_b32_e32 v56, 0, v165, vcc
	v_subb_co_u32_e64 v54, vcc, v54, v55, s[34:35]
	v_cmp_lt_i32_e32 vcc, 0, v53
	v_cndmask_b32_e64 v57, 0, 1, s[20:21]
	v_cmp_eq_u32_e64 s[20:21], s46, v59
	v_cndmask_b32_e64 v55, 0, 1, vcc
	v_cndmask_b32_e64 v55, v57, v55, s[34:35]
	v_and_b32_e32 v55, 1, v55
	v_cmp_eq_u32_e64 s[24:25], s0, v59
	v_cmp_eq_u32_e32 vcc, 1, v55
	s_or_b64 s[6:7], s[24:25], s[20:21]
	s_or_b64 vcc, s[6:7], vcc
	v_cndmask_b32_e32 v55, 0, v166, vcc
	v_subb_co_u32_e64 v53, vcc, v53, v81, s[28:29]
	v_cmp_lt_i32_e32 vcc, 0, v54
	v_or3_b32 v52, v52, v56, v55
	v_cmp_eq_u32_e64 s[20:21], s46, v60
	v_cndmask_b32_e64 v56, 0, 1, vcc
	v_cndmask_b32_e64 v56, v71, v56, s[28:29]
	v_and_b32_e32 v56, 1, v56
	v_cmp_eq_u32_e64 s[24:25], s0, v60
	v_cmp_eq_u32_e32 vcc, 1, v56
	s_or_b64 s[6:7], s[24:25], s[20:21]
	v_cndmask_b32_e64 v55, 0, 1, s[28:29]
	s_or_b64 vcc, s[6:7], vcc
	v_cndmask_b32_e32 v56, 0, v167, vcc
	v_subb_co_u32_e64 v54, vcc, v54, v55, s[26:27]
	v_cmp_lt_i32_e32 vcc, 0, v53
	v_cndmask_b32_e64 v57, 0, 1, s[12:13]
	v_cmp_eq_u32_e64 s[12:13], s46, v61
	v_cndmask_b32_e64 v55, 0, 1, vcc
	v_cndmask_b32_e64 v55, v57, v55, s[26:27]
	v_and_b32_e32 v55, 1, v55
	v_cmp_eq_u32_e64 s[20:21], s0, v61
	v_cmp_eq_u32_e32 vcc, 1, v55
	s_or_b64 s[6:7], s[20:21], s[12:13]
	s_or_b64 vcc, s[6:7], vcc
	v_cndmask_b32_e32 v55, 0, v168, vcc
	v_subb_co_u32_e64 v53, vcc, v53, v82, s[22:23]
	v_cmp_lt_i32_e32 vcc, 0, v54
	v_or3_b32 v52, v52, v56, v55
	v_cmp_eq_u32_e64 s[12:13], s46, v62
	v_cndmask_b32_e64 v56, 0, 1, vcc
	v_cndmask_b32_e64 v56, v72, v56, s[22:23]
	v_and_b32_e32 v56, 1, v56
	v_cmp_eq_u32_e64 s[20:21], s0, v62
	v_cmp_eq_u32_e32 vcc, 1, v56
	s_or_b64 s[6:7], s[20:21], s[12:13]
	v_cndmask_b32_e64 v55, 0, 1, s[22:23]
	s_or_b64 vcc, s[6:7], vcc
	v_cndmask_b32_e32 v56, 0, v169, vcc
	v_subb_co_u32_e64 v54, vcc, v54, v55, s[18:19]
	v_cmp_lt_i32_e32 vcc, 0, v53
	v_cndmask_b32_e64 v57, 0, 1, s[10:11]
	v_cmp_eq_u32_e64 s[10:11], s46, v63
	v_cndmask_b32_e64 v55, 0, 1, vcc
	v_cndmask_b32_e64 v55, v57, v55, s[18:19]
	v_and_b32_e32 v55, 1, v55
	v_cmp_eq_u32_e64 s[12:13], s0, v63
	v_cmp_eq_u32_e32 vcc, 1, v55
	s_or_b64 s[6:7], s[12:13], s[10:11]
	s_or_b64 vcc, s[6:7], vcc
	v_cndmask_b32_e32 v55, 0, v170, vcc
	v_subb_co_u32_e64 v53, vcc, v53, v87, s[16:17]
	v_cmp_lt_i32_e32 vcc, 0, v54
	v_cmp_eq_u32_e64 s[10:11], s46, v64
	v_cmp_eq_u32_e64 s[12:13], s0, v64
	v_cndmask_b32_e64 v54, 0, 1, vcc
	v_cndmask_b32_e64 v54, v73, v54, s[16:17]
	v_and_b32_e32 v54, 1, v54
	v_cmp_eq_u32_e32 vcc, 1, v54
	s_or_b64 s[6:7], s[12:13], s[10:11]
	s_or_b64 vcc, s[6:7], vcc
	v_cndmask_b32_e32 v54, 0, v171, vcc
	v_cmp_lt_i32_e32 vcc, 0, v53
	v_or3_b32 v52, v52, v56, v55
	v_cndmask_b32_e64 v55, 0, 1, s[14:15]
	v_cndmask_b32_e64 v53, 0, 1, vcc
	v_cndmask_b32_e64 v53, v55, v53, s[8:9]
	v_and_b32_e32 v53, 1, v53
	v_cmp_eq_u32_e64 s[8:9], s46, v65
	v_cmp_eq_u32_e64 s[10:11], s0, v65
	v_cmp_eq_u32_e32 vcc, 1, v53
	s_or_b64 s[6:7], s[10:11], s[8:9]
	s_or_b64 vcc, s[6:7], vcc
	v_cndmask_b32_e32 v53, 0, v172, vcc
	v_readlane_b32 s52, v253, 51
	v_readlane_b32 s56, v253, 30
	v_readlane_b32 s50, v253, 55
	v_readlane_b32 s78, v253, 58
	v_or3_b32 v52, v52, v54, v53
	s_mov_b64 s[8:9], 0
	v_readlane_b32 s83, v252, 3
	v_readlane_b32 s88, v253, 40
	v_readlane_b32 s97, v253, 43
	v_readlane_b32 s71, v253, 18
	v_readlane_b32 s69, v253, 1
	v_readlane_b32 s67, v253, 44
	v_readlane_b32 s72, v253, 45
	v_readlane_b32 s73, v253, 46
	v_readlane_b32 s74, v253, 47
	v_readlane_b32 s75, v253, 48
	v_readlane_b32 s76, v253, 49
	v_readlane_b32 s77, v253, 50
	v_readlane_b32 s53, v253, 52
	v_readlane_b32 s57, v253, 31
	v_readlane_b32 s85, v253, 54
	v_readlane_b32 s51, v253, 56
	v_readlane_b32 s54, v253, 57
	v_readlane_b32 s79, v253, 59
	v_readlane_b32 s55, v253, 60
	v_readlane_b32 s58, v253, 61
	v_readlane_b32 s59, v253, 62
	s_movk_i32 s60, 0x1200
	v_readlane_b32 s61, v253, 63
	s_mov_b64 s[62:63], 0x2000
	s_mov_b32 s64, 0x3fb8aa3b
	v_readlane_b32 s65, v252, 0
	s_mov_b64 s[2:3], 0x6000
	s_movk_i32 s66, 0x204
	v_readlane_b32 s86, v252, 1
	v_readlane_b32 s87, v252, 5
	v_readlane_b32 s36, v252, 4
	v_readlane_b32 s89, v253, 41
